# grid barrier: all workgroups poll the top-level generation word directly; per-XCD generation hop and its atomic removed
# baseline (speedup 1.0000x reference)
.LBB0_115:
	s_or_b64 exec, exec, s[8:9]
	v_cvt_f32_u32_e32 v5, v3
	s_waitcnt vmcnt(0)
	v_readfirstlane_b32 s6, v4
	v_sub_u32_e32 v4, 0, v3
	v_rcp_iflag_f32_e32 v5, v5
	v_add_u32_e32 v6, s6, v0
	v_mul_f32_e32 v5, 0x4f7ffffe, v5
	v_cvt_u32_f32_e32 v5, v5
	v_mul_lo_u32 v0, v4, v5
	v_mul_hi_u32 v0, v5, v0
	v_add_u32_e32 v0, v5, v0
	v_mul_hi_u32 v0, v6, v0
	v_mul_lo_u32 v4, v0, v3
	v_sub_u32_e32 v4, v6, v4
	v_add_u32_e32 v5, 1, v0
	v_cmp_ge_u32_e32 vcc, v4, v3
	s_nop 1
	v_cndmask_b32_e32 v0, v0, v5, vcc
	v_sub_u32_e32 v5, v4, v3
	v_cndmask_b32_e32 v4, v4, v5, vcc
	v_add_u32_e32 v5, 1, v0
	v_cmp_ge_u32_e32 vcc, v4, v3
	v_add_u32_e32 v4, 1, v6
	s_nop 0
	v_cndmask_b32_e32 v0, v0, v5, vcc
	v_mul_lo_u32 v5, v3, v0
	v_add_u32_e32 v3, v5, v3
	v_cmp_ne_u32_e32 vcc, v4, v3
	s_and_saveexec_b64 s[6:7], vcc
	s_xor_b64 s[6:7], exec, s[6:7]
	s_cbranch_execz .LBB0_129
	s_waitcnt lgkmcnt(0)
	s_add_u32 s12, s52, 0x14e2b500
	s_addc_u32 s13, s53, 0
	v_mov_b32_e32 v2, 0
	global_load_dword v2, v2, s[12:13] sc1
	s_waitcnt vmcnt(0)
	v_cmp_eq_u32_e32 vcc, v2, v0
	s_and_saveexec_b64 s[8:9], vcc
	s_cbranch_execz .LBB0_128
	s_add_u32 s10, s52, 0x14e28200
	s_addc_u32 s11, s53, 0
	s_mov_b32 s26, 1
	s_mov_b64 s[14:15], 0
	v_mov_b32_e32 v2, 0
	s_branch .LBB0_119

.LBB0_146:
	s_or_b64 exec, exec, s[6:7]
	s_mov_b64 s[6:7], exec
	v_mbcnt_lo_u32_b32 v0, s6, 0
	v_mbcnt_hi_u32_b32 v0, s7, v0
	v_cmp_eq_u32_e32 vcc, 0, v0
	s_waitcnt vmcnt(0)
	buffer_inv sc1
	s_and_saveexec_b64 s[8:9], vcc
	s_cbranch_execz .LBB0_148
	s_bcnt1_i32_b64 s6, s[6:7]
	v_mov_b32_e32 v0, 0x2000
	v_mov_b32_e32 v2, s6
.LBB0_148:
	s_or_b64 exec, exec, s[8:9]
	s_waitcnt vmcnt(0)

.LBB0_218:
	s_or_b64 exec, exec, s[10:11]
	v_cvt_f32_u32_e32 v4, v2
	s_waitcnt vmcnt(0)
	v_readfirstlane_b32 s8, v3
	v_sub_u32_e32 v3, 0, v2
	v_rcp_iflag_f32_e32 v4, v4
	v_add_u32_e32 v5, s8, v0
	v_mul_f32_e32 v4, 0x4f7ffffe, v4
	v_cvt_u32_f32_e32 v4, v4
	v_mul_lo_u32 v0, v3, v4
	v_mul_hi_u32 v0, v4, v0
	v_add_u32_e32 v0, v4, v0
	v_mul_hi_u32 v0, v5, v0
	v_mul_lo_u32 v3, v0, v2
	v_sub_u32_e32 v3, v5, v3
	v_add_u32_e32 v4, 1, v0
	v_cmp_ge_u32_e32 vcc, v3, v2
	s_nop 1
	v_cndmask_b32_e32 v0, v0, v4, vcc
	v_sub_u32_e32 v4, v3, v2
	v_cndmask_b32_e32 v3, v3, v4, vcc
	v_add_u32_e32 v4, 1, v0
	v_cmp_ge_u32_e32 vcc, v3, v2
	v_add_u32_e32 v3, 1, v5
	s_nop 0
	v_cndmask_b32_e32 v0, v0, v4, vcc
	v_mul_lo_u32 v4, v2, v0
	v_add_u32_e32 v2, v4, v2
	v_cmp_ne_u32_e32 vcc, v3, v2
	s_and_saveexec_b64 s[8:9], vcc
	s_xor_b64 s[8:9], exec, s[8:9]
	s_cbranch_execz .LBB0_232
	s_waitcnt lgkmcnt(0)
	s_add_u32 s14, s52, 0x14e2b500
	s_addc_u32 s15, s53, 0
	v_mov_b32_e32 v1, 0
	global_load_dword v1, v1, s[14:15] sc1
	s_waitcnt vmcnt(0)
	v_cmp_eq_u32_e32 vcc, v1, v0
	s_and_saveexec_b64 s[10:11], vcc
	s_cbranch_execz .LBB0_231
	s_add_u32 s12, s52, 0x14e28200
	s_addc_u32 s13, s53, 0
	s_mov_b32 s26, 1
	s_mov_b64 s[16:17], 0
	v_mov_b32_e32 v1, 0
	s_branch .LBB0_222

.LBB0_249:
	s_or_b64 exec, exec, s[8:9]
	s_mov_b64 s[8:9], exec
	v_mbcnt_lo_u32_b32 v0, s8, 0
	v_mbcnt_hi_u32_b32 v0, s9, v0
	v_cmp_eq_u32_e32 vcc, 0, v0
	s_waitcnt vmcnt(0)
	buffer_inv sc1
	s_and_saveexec_b64 s[10:11], vcc
	s_cbranch_execz .LBB0_251
	s_bcnt1_i32_b64 s8, s[8:9]
	v_mov_b32_e32 v0, 0x2000
	v_mov_b32_e32 v1, s8
.LBB0_251:
	s_or_b64 exec, exec, s[10:11]
	s_waitcnt vmcnt(0)

.LBB0_341:
	s_or_b64 exec, exec, s[8:9]
	s_mov_b64 s[8:9], exec
	v_mbcnt_lo_u32_b32 v0, s8, 0
	v_mbcnt_hi_u32_b32 v0, s9, v0
	v_cmp_eq_u32_e32 vcc, 0, v0
	s_waitcnt vmcnt(0)
	buffer_inv sc1
	s_and_saveexec_b64 s[10:11], vcc
	s_cbranch_execz .LBB0_343
	s_bcnt1_i32_b64 s8, s[8:9]
	v_mov_b32_e32 v0, 0x2000
	v_mov_b32_e32 v1, s8
.LBB0_343:
	s_or_b64 exec, exec, s[10:11]
	s_waitcnt vmcnt(0)

.LBB0_411:
	s_or_b64 exec, exec, s[8:9]
	s_mov_b64 s[8:9], exec
	v_mbcnt_lo_u32_b32 v0, s8, 0
	v_mbcnt_hi_u32_b32 v0, s9, v0
	v_cmp_eq_u32_e32 vcc, 0, v0
	s_waitcnt vmcnt(0)
	buffer_inv sc1
	s_and_saveexec_b64 s[10:11], vcc
	s_cbranch_execz .LBB0_413
	s_bcnt1_i32_b64 s8, s[8:9]
	v_mov_b32_e32 v0, 0x2000
	v_mov_b32_e32 v1, s8
.LBB0_413:
	s_or_b64 exec, exec, s[10:11]
	s_waitcnt vmcnt(0)

.LBB0_500:
	s_or_b64 exec, exec, s[8:9]
	s_mov_b64 s[8:9], exec
	v_mbcnt_lo_u32_b32 v0, s8, 0
	v_mbcnt_hi_u32_b32 v0, s9, v0
	v_cmp_eq_u32_e32 vcc, 0, v0
	s_waitcnt vmcnt(0)
	buffer_inv sc1
	s_and_saveexec_b64 s[10:11], vcc
	s_cbranch_execz .LBB0_502
	s_bcnt1_i32_b64 s8, s[8:9]
	v_mov_b32_e32 v0, 0x2000
	v_mov_b32_e32 v1, s8
.LBB0_502:
	s_or_b64 exec, exec, s[10:11]
	s_waitcnt vmcnt(0)

.LBB0_596:
	s_or_b64 exec, exec, s[8:9]
	s_mov_b64 s[8:9], exec
	v_mbcnt_lo_u32_b32 v0, s8, 0
	v_mbcnt_hi_u32_b32 v0, s9, v0
	v_cmp_eq_u32_e32 vcc, 0, v0
	s_waitcnt vmcnt(0)
	buffer_inv sc1
	s_and_saveexec_b64 s[10:11], vcc
	s_cbranch_execz .LBB0_598
	s_bcnt1_i32_b64 s8, s[8:9]
	v_mov_b32_e32 v0, 0x2000
	v_mov_b32_e32 v1, s8
.LBB0_598:
	s_or_b64 exec, exec, s[10:11]
	s_waitcnt vmcnt(0)

.LBB0_670:
	s_or_b64 exec, exec, s[8:9]
	s_mov_b64 s[8:9], exec
	v_mbcnt_lo_u32_b32 v0, s8, 0
	v_mbcnt_hi_u32_b32 v0, s9, v0
	v_cmp_eq_u32_e32 vcc, 0, v0
	s_waitcnt vmcnt(0)
	buffer_inv sc1
	s_and_saveexec_b64 s[10:11], vcc
	s_cbranch_execz .LBB0_672
	s_bcnt1_i32_b64 s8, s[8:9]
	v_mov_b32_e32 v0, 0x2000
	v_mov_b32_e32 v1, s8
.LBB0_672:
	s_or_b64 exec, exec, s[10:11]
	s_waitcnt vmcnt(0)

.LBB0_761:
	s_or_b64 exec, exec, s[8:9]
	s_mov_b64 s[8:9], exec
	v_mbcnt_lo_u32_b32 v0, s8, 0
	v_mbcnt_hi_u32_b32 v0, s9, v0
	v_cmp_eq_u32_e32 vcc, 0, v0
	s_waitcnt vmcnt(0)
	buffer_inv sc1
	s_and_saveexec_b64 s[10:11], vcc
	s_cbranch_execz .LBB0_763
	s_bcnt1_i32_b64 s8, s[8:9]
	v_mov_b32_e32 v0, 0x2000
	v_mov_b32_e32 v1, s8
.LBB0_763:
	s_or_b64 exec, exec, s[10:11]
	s_waitcnt vmcnt(0)

.LBB0_864:
	s_or_b64 exec, exec, s[8:9]
	s_mov_b64 s[8:9], exec
	v_mbcnt_lo_u32_b32 v0, s8, 0
	v_mbcnt_hi_u32_b32 v0, s9, v0
	v_cmp_eq_u32_e32 vcc, 0, v0
	s_waitcnt vmcnt(0)
	buffer_inv sc1
	s_and_saveexec_b64 s[10:11], vcc
	s_cbranch_execz .LBB0_866
	s_bcnt1_i32_b64 s8, s[8:9]
	v_mov_b32_e32 v0, 0x2000
	v_mov_b32_e32 v1, s8
.LBB0_866:
	s_or_b64 exec, exec, s[10:11]
	s_waitcnt vmcnt(0)

.LBB0_924:
	s_or_b64 exec, exec, s[12:13]
	v_cvt_f32_u32_e32 v4, v2
	s_waitcnt vmcnt(0)
	v_readfirstlane_b32 s10, v3
	v_sub_u32_e32 v3, 0, v2
	v_rcp_iflag_f32_e32 v4, v4
	v_add_u32_e32 v5, s10, v0
	v_mul_f32_e32 v4, 0x4f7ffffe, v4
	v_cvt_u32_f32_e32 v4, v4
	v_mul_lo_u32 v0, v3, v4
	v_mul_hi_u32 v0, v4, v0
	v_add_u32_e32 v0, v4, v0
	v_mul_hi_u32 v0, v5, v0
	v_mul_lo_u32 v3, v0, v2
	v_sub_u32_e32 v3, v5, v3
	v_add_u32_e32 v4, 1, v0
	v_cmp_ge_u32_e32 vcc, v3, v2
	s_nop 1
	v_cndmask_b32_e32 v0, v0, v4, vcc
	v_sub_u32_e32 v4, v3, v2
	v_cndmask_b32_e32 v3, v3, v4, vcc
	v_add_u32_e32 v4, 1, v0
	v_cmp_ge_u32_e32 vcc, v3, v2
	v_add_u32_e32 v3, 1, v5
	s_nop 0
	v_cndmask_b32_e32 v0, v0, v4, vcc
	v_mul_lo_u32 v4, v2, v0
	v_add_u32_e32 v2, v4, v2
	v_cmp_ne_u32_e32 vcc, v3, v2
	s_and_saveexec_b64 s[10:11], vcc
	s_xor_b64 s[10:11], exec, s[10:11]
	s_cbranch_execz .LBB0_938
	s_waitcnt lgkmcnt(0)
	s_add_u32 s16, s52, 0x14e2b500
	s_addc_u32 s17, s53, 0
	v_mov_b32_e32 v1, 0
	global_load_dword v1, v1, s[16:17] sc1
	s_waitcnt vmcnt(0)
	v_cmp_eq_u32_e32 vcc, v1, v0
	s_and_saveexec_b64 s[12:13], vcc
	s_cbranch_execz .LBB0_937
	s_add_u32 s14, s52, 0x14e28200
	s_addc_u32 s15, s53, 0
	s_mov_b32 s28, 1
	s_mov_b64 s[18:19], 0
	v_mov_b32_e32 v1, 0
	s_branch .LBB0_928

.LBB0_955:
	s_or_b64 exec, exec, s[10:11]
	s_mov_b64 s[10:11], exec
	v_mbcnt_lo_u32_b32 v0, s10, 0
	v_mbcnt_hi_u32_b32 v0, s11, v0
	v_cmp_eq_u32_e32 vcc, 0, v0
	s_waitcnt vmcnt(0)
	buffer_inv sc1
	s_and_saveexec_b64 s[12:13], vcc
	s_cbranch_execz .LBB0_957
	s_bcnt1_i32_b64 s10, s[10:11]
	v_mov_b32_e32 v0, 0x2000
	v_mov_b32_e32 v1, s10
.LBB0_957:
	s_or_b64 exec, exec, s[12:13]
	s_waitcnt vmcnt(0)

.LBB0_1489:
	s_or_b64 exec, exec, s[10:11]
	v_cvt_f32_u32_e32 v4, v2
	s_waitcnt vmcnt(0)
	v_readfirstlane_b32 s8, v3
	v_sub_u32_e32 v3, 0, v2
	v_rcp_iflag_f32_e32 v4, v4
	v_add_u32_e32 v5, s8, v0
	v_mul_f32_e32 v4, 0x4f7ffffe, v4
	v_cvt_u32_f32_e32 v4, v4
	v_mul_lo_u32 v0, v3, v4
	v_mul_hi_u32 v0, v4, v0
	v_add_u32_e32 v0, v4, v0
	v_mul_hi_u32 v0, v5, v0
	v_mul_lo_u32 v3, v0, v2
	v_sub_u32_e32 v3, v5, v3
	v_add_u32_e32 v4, 1, v0
	v_cmp_ge_u32_e32 vcc, v3, v2
	s_nop 1
	v_cndmask_b32_e32 v0, v0, v4, vcc
	v_sub_u32_e32 v4, v3, v2
	v_cndmask_b32_e32 v3, v3, v4, vcc
	v_add_u32_e32 v4, 1, v0
	v_cmp_ge_u32_e32 vcc, v3, v2
	v_add_u32_e32 v3, 1, v5
	s_nop 0
	v_cndmask_b32_e32 v0, v0, v4, vcc
	v_mul_lo_u32 v4, v2, v0
	v_add_u32_e32 v2, v4, v2
	v_cmp_ne_u32_e32 vcc, v3, v2
	s_and_saveexec_b64 s[8:9], vcc
	s_xor_b64 s[8:9], exec, s[8:9]
	s_cbranch_execz .LBB0_1503
	s_waitcnt lgkmcnt(0)
	s_add_u32 s14, s52, 0x14e2b500
	s_addc_u32 s15, s53, 0
	v_mov_b32_e32 v1, 0
	global_load_dword v1, v1, s[14:15] sc1
	s_waitcnt vmcnt(0)
	v_cmp_eq_u32_e32 vcc, v1, v0
	s_and_saveexec_b64 s[10:11], vcc
	s_cbranch_execz .LBB0_1502
	s_add_u32 s12, s52, 0x14e28200
	s_addc_u32 s13, s53, 0
	s_mov_b32 s28, 1
	s_mov_b64 s[16:17], 0
	v_mov_b32_e32 v1, 0
	s_branch .LBB0_1493

.LBB0_1520:
	s_or_b64 exec, exec, s[8:9]
	s_mov_b64 s[8:9], exec
	v_mbcnt_lo_u32_b32 v0, s8, 0
	v_mbcnt_hi_u32_b32 v0, s9, v0
	v_cmp_eq_u32_e32 vcc, 0, v0
	s_waitcnt vmcnt(0)
	buffer_inv sc1
	s_and_saveexec_b64 s[10:11], vcc
	s_cbranch_execz .LBB0_1522
	s_bcnt1_i32_b64 s8, s[8:9]
	v_mov_b32_e32 v0, 0x2000
	v_mov_b32_e32 v1, s8
.LBB0_1522:
	s_or_b64 exec, exec, s[10:11]
	s_waitcnt vmcnt(0)

.LBB0_1589:
	s_or_b64 exec, exec, s[10:11]
	s_mov_b64 s[10:11], exec
	v_mbcnt_lo_u32_b32 v0, s10, 0
	v_mbcnt_hi_u32_b32 v0, s11, v0
	v_cmp_eq_u32_e32 vcc, 0, v0
	s_waitcnt vmcnt(0)
	buffer_inv sc1
	s_and_saveexec_b64 s[12:13], vcc
	s_cbranch_execz .LBB0_1591
	s_bcnt1_i32_b64 s10, s[10:11]
	v_mov_b32_e32 v0, 0x2000
	v_mov_b32_e32 v1, s10
.LBB0_1591:
	s_or_b64 exec, exec, s[12:13]
	s_waitcnt vmcnt(0)

.LBB0_1710:
	s_or_b64 exec, exec, s[14:15]
	v_cvt_f32_u32_e32 v4, v2
	s_waitcnt vmcnt(0)
	v_readfirstlane_b32 s12, v3
	v_sub_u32_e32 v3, 0, v2
	v_rcp_iflag_f32_e32 v4, v4
	v_add_u32_e32 v5, s12, v0
	v_mul_f32_e32 v4, 0x4f7ffffe, v4
	v_cvt_u32_f32_e32 v4, v4
	v_mul_lo_u32 v0, v3, v4
	v_mul_hi_u32 v0, v4, v0
	v_add_u32_e32 v0, v4, v0
	v_mul_hi_u32 v0, v5, v0
	v_mul_lo_u32 v3, v0, v2
	v_sub_u32_e32 v3, v5, v3
	v_add_u32_e32 v4, 1, v0
	v_cmp_ge_u32_e32 vcc, v3, v2
	s_nop 1
	v_cndmask_b32_e32 v0, v0, v4, vcc
	v_sub_u32_e32 v4, v3, v2
	v_cndmask_b32_e32 v3, v3, v4, vcc
	v_add_u32_e32 v4, 1, v0
	v_cmp_ge_u32_e32 vcc, v3, v2
	v_add_u32_e32 v3, 1, v5
	s_nop 0
	v_cndmask_b32_e32 v0, v0, v4, vcc
	v_mul_lo_u32 v4, v2, v0
	v_add_u32_e32 v2, v4, v2
	v_cmp_ne_u32_e32 vcc, v3, v2
	s_and_saveexec_b64 s[12:13], vcc
	s_xor_b64 s[12:13], exec, s[12:13]
	s_cbranch_execz .LBB0_1724
	s_waitcnt lgkmcnt(0)
	s_add_u32 s18, s52, 0x14e2b500
	s_addc_u32 s19, s53, 0
	v_mov_b32_e32 v1, 0
	global_load_dword v1, v1, s[18:19] sc1
	s_waitcnt vmcnt(0)
	v_cmp_eq_u32_e32 vcc, v1, v0
	s_and_saveexec_b64 s[14:15], vcc
	s_cbranch_execz .LBB0_1723
	s_add_u32 s16, s52, 0x14e28200
	s_addc_u32 s17, s53, 0
	s_mov_b32 s30, 1
	s_mov_b64 s[20:21], 0
	v_mov_b32_e32 v1, 0
	s_branch .LBB0_1714

.LBB0_1741:
	s_or_b64 exec, exec, s[12:13]
	s_mov_b64 s[12:13], exec
	v_mbcnt_lo_u32_b32 v0, s12, 0
	v_mbcnt_hi_u32_b32 v0, s13, v0
	v_cmp_eq_u32_e32 vcc, 0, v0
	s_waitcnt vmcnt(0)
	buffer_inv sc1
	s_and_saveexec_b64 s[14:15], vcc
	s_cbranch_execz .LBB0_1743
	s_bcnt1_i32_b64 s12, s[12:13]
	v_mov_b32_e32 v0, 0x2000
	v_mov_b32_e32 v1, s12
.LBB0_1743:
	s_or_b64 exec, exec, s[14:15]
	s_waitcnt vmcnt(0)

.LBB0_1801:
	s_or_b64 exec, exec, s[12:13]
	s_mov_b64 s[12:13], exec
	v_mbcnt_lo_u32_b32 v0, s12, 0
	v_mbcnt_hi_u32_b32 v0, s13, v0
	v_cmp_eq_u32_e32 vcc, 0, v0
	s_waitcnt vmcnt(0)
	buffer_inv sc1
	s_and_saveexec_b64 s[14:15], vcc
	s_cbranch_execz .LBB0_1803
	s_bcnt1_i32_b64 s12, s[12:13]
	v_mov_b32_e32 v0, 0x2000
	v_mov_b32_e32 v1, s12
.LBB0_1803:
	s_or_b64 exec, exec, s[14:15]
	s_waitcnt vmcnt(0)

.LBB0_1891:
	s_or_b64 exec, exec, s[10:11]
	s_mov_b64 s[10:11], exec
	v_mbcnt_lo_u32_b32 v0, s10, 0
	v_mbcnt_hi_u32_b32 v0, s11, v0
	v_cmp_eq_u32_e32 vcc, 0, v0
	s_waitcnt vmcnt(0)
	buffer_inv sc1
	s_and_saveexec_b64 s[12:13], vcc
	s_cbranch_execz .LBB0_1893
	s_bcnt1_i32_b64 s10, s[10:11]
	v_mov_b32_e32 v0, 0x2000
	v_mov_b32_e32 v1, s10
.LBB0_1893:
	s_or_b64 exec, exec, s[12:13]
	s_waitcnt vmcnt(0)

.LBB0_1988:
	s_or_b64 exec, exec, s[12:13]
	s_mov_b64 s[12:13], exec
	v_mbcnt_lo_u32_b32 v0, s12, 0
	v_mbcnt_hi_u32_b32 v0, s13, v0
	v_cmp_eq_u32_e32 vcc, 0, v0
	s_waitcnt vmcnt(0)
	buffer_inv sc1
	s_and_saveexec_b64 s[14:15], vcc
	s_cbranch_execz .LBB0_1990
	s_bcnt1_i32_b64 s12, s[12:13]
	v_mov_b32_e32 v0, 0x2000
	v_mov_b32_e32 v1, s12
.LBB0_1990:
	s_or_b64 exec, exec, s[14:15]
	s_waitcnt vmcnt(0)

.LBB0_2063:
	s_or_b64 exec, exec, s[10:11]
	s_mov_b64 s[10:11], exec
	v_mbcnt_lo_u32_b32 v0, s10, 0
	v_mbcnt_hi_u32_b32 v0, s11, v0
	v_cmp_eq_u32_e32 vcc, 0, v0
	s_waitcnt vmcnt(0)
	buffer_inv sc1
	s_and_saveexec_b64 s[12:13], vcc
	s_cbranch_execz .LBB0_2065
	s_bcnt1_i32_b64 s10, s[10:11]
	v_mov_b32_e32 v0, 0x2000
	v_mov_b32_e32 v1, s10
.LBB0_2065:
	s_or_b64 exec, exec, s[12:13]
	s_waitcnt vmcnt(0)

.LBB0_2155:
	s_or_b64 exec, exec, s[10:11]
	s_mov_b64 s[10:11], exec
	v_mbcnt_lo_u32_b32 v0, s10, 0
	v_mbcnt_hi_u32_b32 v0, s11, v0
	v_cmp_eq_u32_e32 vcc, 0, v0
	s_waitcnt vmcnt(0)
	buffer_inv sc1
	s_and_saveexec_b64 s[12:13], vcc
	s_cbranch_execz .LBB0_2157
	s_bcnt1_i32_b64 s10, s[10:11]
	v_mov_b32_e32 v0, 0x2000
	v_mov_b32_e32 v1, s10
.LBB0_2157:
	s_or_b64 exec, exec, s[12:13]
	s_waitcnt vmcnt(0)

.LBB0_2259:
	s_or_b64 exec, exec, s[12:13]
	s_mov_b64 s[12:13], exec
	v_mbcnt_lo_u32_b32 v0, s12, 0
	v_mbcnt_hi_u32_b32 v0, s13, v0
	v_cmp_eq_u32_e32 vcc, 0, v0
	s_waitcnt vmcnt(0)
	buffer_inv sc1
	s_and_saveexec_b64 s[14:15], vcc
	s_cbranch_execz .LBB0_2261
	s_bcnt1_i32_b64 s12, s[12:13]
	v_mov_b32_e32 v0, 0x2000
	v_mov_b32_e32 v1, s12
.LBB0_2261:
	s_or_b64 exec, exec, s[14:15]
	s_waitcnt vmcnt(0)

.LBB0_2327:
	s_or_b64 exec, exec, s[12:13]
	v_cvt_f32_u32_e32 v4, v2
	s_waitcnt vmcnt(0)
	v_readfirstlane_b32 s8, v3
	v_sub_u32_e32 v3, 0, v2
	v_rcp_iflag_f32_e32 v4, v4
	v_add_u32_e32 v5, s8, v0
	v_mul_f32_e32 v4, 0x4f7ffffe, v4
	v_cvt_u32_f32_e32 v4, v4
	v_mul_lo_u32 v0, v3, v4
	v_mul_hi_u32 v0, v4, v0
	v_add_u32_e32 v0, v4, v0
	v_mul_hi_u32 v0, v5, v0
	v_mul_lo_u32 v3, v0, v2
	v_sub_u32_e32 v3, v5, v3
	v_add_u32_e32 v4, 1, v0
	v_cmp_ge_u32_e32 vcc, v3, v2
	s_nop 1
	v_cndmask_b32_e32 v0, v0, v4, vcc
	v_sub_u32_e32 v4, v3, v2
	v_cndmask_b32_e32 v3, v3, v4, vcc
	v_add_u32_e32 v4, 1, v0
	v_cmp_ge_u32_e32 vcc, v3, v2
	v_add_u32_e32 v3, 1, v5
	s_nop 0
	v_cndmask_b32_e32 v0, v0, v4, vcc
	v_mul_lo_u32 v4, v2, v0
	v_add_u32_e32 v2, v4, v2
	v_cmp_ne_u32_e32 vcc, v3, v2
	s_and_saveexec_b64 s[8:9], vcc
	s_xor_b64 s[8:9], exec, s[8:9]
	s_cbranch_execz .LBB0_2341
	s_waitcnt lgkmcnt(0)
	s_add_u32 s16, s52, 0x14e2b500
	s_addc_u32 s17, s53, 0
	v_mov_b32_e32 v1, 0
	global_load_dword v1, v1, s[16:17] sc1
	s_waitcnt vmcnt(0)
	v_cmp_eq_u32_e32 vcc, v1, v0
	s_and_saveexec_b64 s[12:13], vcc
	s_cbranch_execz .LBB0_2340
	s_add_u32 s14, s52, 0x14e28200
	s_addc_u32 s15, s53, 0
	s_mov_b32 s28, 1
	s_mov_b64 s[18:19], 0
	v_mov_b32_e32 v1, 0
	s_branch .LBB0_2331

.LBB0_2358:
	s_or_b64 exec, exec, s[8:9]
	s_mov_b64 s[8:9], exec
	v_mbcnt_lo_u32_b32 v0, s8, 0
	v_mbcnt_hi_u32_b32 v0, s9, v0
	v_cmp_eq_u32_e32 vcc, 0, v0
	s_waitcnt vmcnt(0)
	buffer_inv sc1
	s_and_saveexec_b64 s[12:13], vcc
	s_cbranch_execz .LBB0_2360
	s_bcnt1_i32_b64 s8, s[8:9]
	v_mov_b32_e32 v0, 0x2000
	v_mov_b32_e32 v1, s8
.LBB0_2360:
	s_or_b64 exec, exec, s[12:13]
	s_waitcnt vmcnt(0)

.LBB0_2436:
	s_or_b64 exec, exec, s[12:13]
	s_mov_b64 s[12:13], exec
	v_mbcnt_lo_u32_b32 v0, s12, 0
	v_mbcnt_hi_u32_b32 v0, s13, v0
	v_cmp_eq_u32_e32 vcc, 0, v0
	s_waitcnt vmcnt(0)
	buffer_inv sc1
	s_and_saveexec_b64 s[14:15], vcc
	s_cbranch_execz .LBB0_2438
	s_bcnt1_i32_b64 s12, s[12:13]
	v_mov_b32_e32 v0, 0x2000
	v_mov_b32_e32 v1, s12
.LBB0_2438:
	s_or_b64 exec, exec, s[14:15]
	s_waitcnt vmcnt(0)

.LBB0_2507:
	s_or_b64 exec, exec, s[12:13]
	s_mov_b64 s[12:13], exec
	v_mbcnt_lo_u32_b32 v0, s12, 0
	v_mbcnt_hi_u32_b32 v0, s13, v0
	v_cmp_eq_u32_e32 vcc, 0, v0
	s_waitcnt vmcnt(0)
	buffer_inv sc1
	s_and_saveexec_b64 s[14:15], vcc
	s_cbranch_execz .LBB0_2509
	s_bcnt1_i32_b64 s12, s[12:13]
	v_mov_b32_e32 v0, 0x2000
	v_mov_b32_e32 v1, s12
.LBB0_2509:
	s_or_b64 exec, exec, s[14:15]
	s_waitcnt vmcnt(0)

.LBB0_2597:
	s_or_b64 exec, exec, s[10:11]
	s_mov_b64 s[10:11], exec
	v_mbcnt_lo_u32_b32 v0, s10, 0
	v_mbcnt_hi_u32_b32 v0, s11, v0
	v_cmp_eq_u32_e32 vcc, 0, v0
	s_waitcnt vmcnt(0)
	buffer_inv sc1
	s_and_saveexec_b64 s[12:13], vcc
	s_cbranch_execz .LBB0_2599
	s_bcnt1_i32_b64 s10, s[10:11]
	v_mov_b32_e32 v0, 0x2000
	v_mov_b32_e32 v1, s10
.LBB0_2599:
	s_or_b64 exec, exec, s[12:13]
	s_waitcnt vmcnt(0)

.LBB0_2694:
	s_or_b64 exec, exec, s[12:13]
	s_mov_b64 s[12:13], exec
	v_mbcnt_lo_u32_b32 v0, s12, 0
	v_mbcnt_hi_u32_b32 v0, s13, v0
	v_cmp_eq_u32_e32 vcc, 0, v0
	s_waitcnt vmcnt(0)
	buffer_inv sc1
	s_and_saveexec_b64 s[14:15], vcc
	s_cbranch_execz .LBB0_2696
	s_bcnt1_i32_b64 s12, s[12:13]
	v_mov_b32_e32 v0, 0x2000
	v_mov_b32_e32 v1, s12
.LBB0_2696:
	s_or_b64 exec, exec, s[14:15]
	s_waitcnt vmcnt(0)

.LBB0_2769:
	s_or_b64 exec, exec, s[10:11]
	s_mov_b64 s[10:11], exec
	v_mbcnt_lo_u32_b32 v0, s10, 0
	v_mbcnt_hi_u32_b32 v0, s11, v0
	v_cmp_eq_u32_e32 vcc, 0, v0
	s_waitcnt vmcnt(0)
	buffer_inv sc1
	s_and_saveexec_b64 s[12:13], vcc
	s_cbranch_execz .LBB0_2771
	s_bcnt1_i32_b64 s10, s[10:11]
	v_mov_b32_e32 v0, 0x2000
	v_mov_b32_e32 v1, s10
.LBB0_2771:
	s_or_b64 exec, exec, s[12:13]
	s_waitcnt vmcnt(0)

.LBB0_2861:
	s_or_b64 exec, exec, s[10:11]
	s_mov_b64 s[10:11], exec
	v_mbcnt_lo_u32_b32 v0, s10, 0
	v_mbcnt_hi_u32_b32 v0, s11, v0
	v_cmp_eq_u32_e32 vcc, 0, v0
	s_waitcnt vmcnt(0)
	buffer_inv sc1
	s_and_saveexec_b64 s[12:13], vcc
	s_cbranch_execz .LBB0_2863
	s_bcnt1_i32_b64 s10, s[10:11]
	v_mov_b32_e32 v0, 0x2000
	v_mov_b32_e32 v1, s10
.LBB0_2863:
	s_or_b64 exec, exec, s[12:13]
	s_waitcnt vmcnt(0)

.LBB0_2965:
	s_or_b64 exec, exec, s[12:13]
	s_mov_b64 s[12:13], exec
	v_mbcnt_lo_u32_b32 v0, s12, 0
	v_mbcnt_hi_u32_b32 v0, s13, v0
	v_cmp_eq_u32_e32 vcc, 0, v0
	s_waitcnt vmcnt(0)
	buffer_inv sc1
	s_and_saveexec_b64 s[14:15], vcc
	s_cbranch_execz .LBB0_2967
	s_bcnt1_i32_b64 s12, s[12:13]
	v_mov_b32_e32 v0, 0x2000
	v_mov_b32_e32 v1, s12
.LBB0_2967:
	s_or_b64 exec, exec, s[14:15]
	s_waitcnt vmcnt(0)

.LBB0_3078:
	s_or_b64 exec, exec, s[10:11]
	s_mov_b64 s[10:11], exec
	v_mbcnt_lo_u32_b32 v0, s10, 0
	v_mbcnt_hi_u32_b32 v0, s11, v0
	v_cmp_eq_u32_e32 vcc, 0, v0
	s_waitcnt vmcnt(0)
	buffer_inv sc1
	s_and_saveexec_b64 s[12:13], vcc
	s_cbranch_execz .LBB0_3080
	s_bcnt1_i32_b64 s10, s[10:11]
	v_mov_b32_e32 v0, 0x2000
	v_mov_b32_e32 v1, s10
.LBB0_3080:
	s_or_b64 exec, exec, s[12:13]
	s_waitcnt vmcnt(0)

.LBB0_3150:
	s_or_b64 exec, exec, s[10:11]
	s_mov_b64 s[10:11], exec
	v_mbcnt_lo_u32_b32 v0, s10, 0
	v_mbcnt_hi_u32_b32 v0, s11, v0
	v_cmp_eq_u32_e32 vcc, 0, v0
	s_waitcnt vmcnt(0)
	buffer_inv sc1
	s_and_saveexec_b64 s[12:13], vcc
	s_cbranch_execz .LBB0_3152
	s_bcnt1_i32_b64 s10, s[10:11]
	v_mov_b32_e32 v0, 0x2000
	v_mov_b32_e32 v1, s10
.LBB0_3152:
	s_or_b64 exec, exec, s[12:13]
	s_waitcnt vmcnt(0)

.LBB0_3212:
	s_or_b64 exec, exec, s[12:13]
	s_mov_b64 s[12:13], exec
	v_mbcnt_lo_u32_b32 v0, s12, 0
	v_mbcnt_hi_u32_b32 v0, s13, v0
	v_cmp_eq_u32_e32 vcc, 0, v0
	s_waitcnt vmcnt(0)
	buffer_inv sc1
	s_and_saveexec_b64 s[14:15], vcc
	s_cbranch_execz .LBB0_3214
	s_bcnt1_i32_b64 s12, s[12:13]
	v_mov_b32_e32 v0, 0x2000
	v_mov_b32_e32 v1, s12
.LBB0_3214:
	s_or_b64 exec, exec, s[14:15]
	s_waitcnt vmcnt(0)

.LBB0_3285:
	s_or_b64 exec, exec, s[10:11]
	s_mov_b64 s[10:11], exec
	v_mbcnt_lo_u32_b32 v0, s10, 0
	v_mbcnt_hi_u32_b32 v0, s11, v0
	v_cmp_eq_u32_e32 vcc, 0, v0
	s_waitcnt vmcnt(0)
	buffer_inv sc1
	s_and_saveexec_b64 s[12:13], vcc
	s_cbranch_execz .LBB0_3287
	s_bcnt1_i32_b64 s10, s[10:11]
	v_mov_b32_e32 v0, 0x2000
	v_mov_b32_e32 v1, s10
.LBB0_3287:
	s_or_b64 exec, exec, s[12:13]
	s_waitcnt vmcnt(0)

.LBB0_3378:
	s_or_b64 exec, exec, s[12:13]
	s_mov_b64 s[12:13], exec
	v_mbcnt_lo_u32_b32 v0, s12, 0
	v_mbcnt_hi_u32_b32 v0, s13, v0
	v_cmp_eq_u32_e32 vcc, 0, v0
	s_waitcnt vmcnt(0)
	buffer_inv sc1
	s_and_saveexec_b64 s[14:15], vcc
	s_cbranch_execz .LBB0_3380
	s_bcnt1_i32_b64 s12, s[12:13]
	v_mov_b32_e32 v0, 0x2000
	v_mov_b32_e32 v1, s12
.LBB0_3380:
	s_or_b64 exec, exec, s[14:15]
	s_waitcnt vmcnt(0)

.LBB0_3453:
	s_or_b64 exec, exec, s[10:11]
	s_mov_b64 s[10:11], exec
	v_mbcnt_lo_u32_b32 v0, s10, 0
	v_mbcnt_hi_u32_b32 v0, s11, v0
	v_cmp_eq_u32_e32 vcc, 0, v0
	s_waitcnt vmcnt(0)
	buffer_inv sc1
	s_and_saveexec_b64 s[12:13], vcc
	s_cbranch_execz .LBB0_3455
	s_bcnt1_i32_b64 s10, s[10:11]
	v_mov_b32_e32 v0, 0x2000
	v_mov_b32_e32 v1, s10
.LBB0_3455:
	s_or_b64 exec, exec, s[12:13]
	s_waitcnt vmcnt(0)

.LBB0_3526:
	s_or_b64 exec, exec, s[10:11]
	s_mov_b64 s[10:11], exec
	v_mbcnt_lo_u32_b32 v0, s10, 0
	v_mbcnt_hi_u32_b32 v0, s11, v0
	v_cmp_eq_u32_e32 vcc, 0, v0
	s_waitcnt vmcnt(0)
	buffer_inv sc1
	s_and_saveexec_b64 s[12:13], vcc
	s_cbranch_execz .LBB0_3528
	s_bcnt1_i32_b64 s10, s[10:11]
	v_mov_b32_e32 v0, 0x2000
	v_mov_b32_e32 v1, s10
.LBB0_3528:
	s_or_b64 exec, exec, s[12:13]
	s_waitcnt vmcnt(0)

.LBB0_3555:
	s_or_b64 exec, exec, s[4:5]
	v_cvt_f32_u32_e32 v4, v2
	s_waitcnt vmcnt(0)
	v_readfirstlane_b32 s2, v3
	v_sub_u32_e32 v3, 0, v2
	v_rcp_iflag_f32_e32 v4, v4
	v_add_u32_e32 v5, s2, v0
	v_mul_f32_e32 v4, 0x4f7ffffe, v4
	v_cvt_u32_f32_e32 v4, v4
	v_mul_lo_u32 v0, v3, v4
	v_mul_hi_u32 v0, v4, v0
	v_add_u32_e32 v0, v4, v0
	v_mul_hi_u32 v0, v5, v0
	v_mul_lo_u32 v3, v0, v2
	v_sub_u32_e32 v3, v5, v3
	v_add_u32_e32 v4, 1, v0
	v_cmp_ge_u32_e32 vcc, v3, v2
	s_nop 1
	v_cndmask_b32_e32 v0, v0, v4, vcc
	v_sub_u32_e32 v4, v3, v2
	v_cndmask_b32_e32 v3, v3, v4, vcc
	v_add_u32_e32 v4, 1, v0
	v_cmp_ge_u32_e32 vcc, v3, v2
	v_add_u32_e32 v3, 1, v5
	s_nop 0
	v_cndmask_b32_e32 v0, v0, v4, vcc
	v_mul_lo_u32 v4, v2, v0
	v_add_u32_e32 v2, v4, v2
	v_cmp_ne_u32_e32 vcc, v3, v2
	s_and_saveexec_b64 s[2:3], vcc
	s_xor_b64 s[2:3], exec, s[2:3]
	s_cbranch_execz .LBB0_3569
	s_waitcnt lgkmcnt(0)
	s_add_u32 s8, s52, 0x14e2b500
	s_addc_u32 s9, s53, 0
	v_mov_b32_e32 v1, 0
	global_load_dword v1, v1, s[8:9] sc1
	s_waitcnt vmcnt(0)
	v_cmp_eq_u32_e32 vcc, v1, v0
	s_and_saveexec_b64 s[4:5], vcc
	s_cbranch_execz .LBB0_3568
	s_add_u32 s6, s52, 0x14e28200
	s_addc_u32 s7, s53, 0
	s_mov_b32 s20, 1
	s_mov_b64 s[10:11], 0
	v_mov_b32_e32 v1, 0
	s_branch .LBB0_3559

.LBB0_3586:
	s_or_b64 exec, exec, s[2:3]
	s_mov_b64 s[2:3], exec
	v_mbcnt_lo_u32_b32 v0, s2, 0
	v_mbcnt_hi_u32_b32 v0, s3, v0
	v_cmp_eq_u32_e32 vcc, 0, v0
	s_waitcnt vmcnt(0)
	buffer_inv sc1
	s_and_saveexec_b64 s[4:5], vcc
	s_cbranch_execz .LBB0_3588
	s_bcnt1_i32_b64 s2, s[2:3]
	v_mov_b32_e32 v0, 0x2000
	v_mov_b32_e32 v1, s2
.LBB0_3588:
	s_or_b64 exec, exec, s[4:5]
	s_waitcnt vmcnt(0)
